# modulated-norm pass: the twelve g/scale/shift loads of a row issued together with counted vmcnt waits
# speedup vs baseline: 1.0088x; 1.0088x over previous
; #define GAS __attribute__((address_space(1)))
; __device__ __forceinline__ unsigned pk2(float lo, float hi) { f32x2_t v = {lo, hi}; bf16x2_t b = __builtin_convertvector(v, bf16x2_t); return __builtin_bit_cast(unsigned, b); }
; #define MN_LOAD(DST, M) do { const int m_ = (M); if (m_ < nrows) { const float* xrow = m_ < NPR ? xP + (size_t)m_ * DM : xS + (size_t)(m_ - NPR) * DM; const GAS f32x4* xr = (const GAS f32x4*)xrow + lane; \
;             _Pragma("unroll") for (int j = 0; j < 4; ++j) DST[j] = __builtin_nontemporal_load(xr + 64 * j); } } while (0)
; #define MOD WSP(float, WS_MOD)
; __device__ __forceinline__ void modnorm_rows(Frame& F, const float* xP, const float* xS, const float* g, const float* MOD, int sh_off, int sc_off, bf16* H, const int nrows) {
;     ...
;     for (int m = gw; m < nrows; m += NGW) {
; #pragma unroll
;         for (int j = 0; j < 4; ++j) { v[j] = n1[j]; n1[j] = n2[j]; }
;         MN_LOAD(n2, m + 2 * NGW);
;         const float* modr = MOD + (size_t)modrow(m) * NMOD;
;         float ss = 0.f;
; #pragma unroll
;         for (int j = 0; j < 4; ++j) ss += (v[j][0] * v[j][0] + v[j][1] * v[j][1]) + (v[j][2] * v[j][2] + v[j][3] * v[j][3]);
;         const float rstd = 1.f / sqrtf(wave_sum(ss) * (1.f / DM) + EPS);
;         GAS v2u* o8 = (GAS v2u*)(H + (size_t)m * DM) + lane;
; #pragma unroll
;         for (int j = 0; j < 4; ++j) { const int col = 4 * lane + 256 * j;
;             const f32x4 gg = *(const f32x4*)(g + col), sc = *(const f32x4*)(modr + sc_off + col), sh = *(const f32x4*)(modr + sh_off + col);
;             const f32x4 o = (v[j] * rstd) * gg * (sc + 1.f) + sh;
;             v2u w; w.x = pk2(o[0], o[1]); w.y = pk2(o[2], o[3]); o8[64 * j] = w; }
;     }
.LBB0_162:
	s_add_i32 s5, s14, 0xffff8000
	v_pk_mul_f32 v[66:67], v[14:15], v[14:15]
	v_pk_mul_f32 v[68:69], v[16:17], v[16:17]
	v_pk_mul_f32 v[70:71], v[22:23], v[22:23]
	v_pk_mul_f32 v[72:73], v[24:25], v[24:25]
	s_lshr_b32 s5, s5, 3
	v_mov_b32_e32 v74, v70
	v_mov_b32_e32 v75, v73
	v_pk_mov_b32 v[70:71], v[70:71], v[72:73] op_sel:[1,0]
	v_mov_b32_e32 v72, v66
	v_mov_b32_e32 v73, v69
	v_pk_mov_b32 v[66:67], v[66:67], v[68:69] op_sel:[1,0]
	s_ashr_i32 s4, s14, 11
	s_add_i32 s5, s5, 16
	v_pk_add_f32 v[66:67], v[66:67], v[72:73]
	s_cmp_lt_i32 s14, 0x8000
	v_pk_add_f32 v[66:67], v[66:67], v[66:67] op_sel_hi:[0,1]
	s_cselect_b32 s4, s4, s5
	v_mul_f32_e32 v66, v6, v6
	s_mul_hi_i32 s5, s4, 0x6000
	s_mulk_i32 s4, 0x6000
	v_pk_add_f32 v[70:71], v[70:71], v[74:75]
	v_pk_fma_f32 v[68:69], v[6:7], v[6:7], v[66:67] op_sel_hi:[1,1,0]
	v_mul_f32_e32 v66, v8, v8
	v_pk_add_f32 v[70:71], v[70:71], v[70:71] op_sel_hi:[0,1]
	v_pk_fma_f32 v[72:73], v[8:9], v[8:9], v[66:67] op_sel_hi:[1,1,0]
	s_add_u32 s4, s3, s4
	v_mul_f32_e32 v68, v2, v2
	v_mul_f32_e32 v72, v3, v3
	v_mul_f32_e32 v70, v4, v4
	v_mul_f32_e32 v66, v5, v5
	s_addc_u32 s5, s13, s5
	v_pk_add_f32 v[68:69], v[68:69], v[72:73]
	v_pk_add_f32 v[66:67], v[70:71], v[66:67]
	v_lshl_add_u64 v[78:79], v[52:53], 2, s[4:5]
	v_pk_add_f32 v[66:67], v[68:69], v[66:67]
	v_add_co_u32_e32 v80, vcc, s18, v78
	v_add_f32_e32 v82, v66, v67
	global_load_dwordx4 v[66:69], v[54:55], off
	v_addc_co_u32_e32 v81, vcc, 0, v79, vcc
	global_load_dwordx4 v[70:73], v[80:81], off
	global_load_dwordx4 v[74:77], v[78:79], off
	global_load_dwordx4 v[90:93], v[54:55], off offset:1024
	global_load_dwordx4 v[94:97], v[80:81], off offset:1024
	global_load_dwordx4 v[98:101], v[78:79], off offset:1024
	global_load_dwordx4 v[102:105], v[54:55], off offset:2048
	global_load_dwordx4 v[106:109], v[80:81], off offset:2048
	global_load_dwordx4 v[110:113], v[78:79], off offset:2048
	global_load_dwordx4 v[114:117], v[54:55], off offset:3072
	global_load_dwordx4 v[118:121], v[80:81], off offset:3072
	global_load_dwordx4 v[122:125], v[78:79], off offset:3072
	ds_bpermute_b32 v83, v58, v82
	s_ashr_i32 s15, s14, 31
	s_waitcnt lgkmcnt(0)
	v_add_f32_e32 v80, v82, v83
	ds_bpermute_b32 v81, v59, v80
	s_waitcnt lgkmcnt(0)
	v_add_f32_e32 v80, v80, v81
	ds_bpermute_b32 v81, v60, v80
	s_waitcnt lgkmcnt(0)
	v_add_f32_e32 v80, v80, v81
	ds_bpermute_b32 v81, v61, v80
	s_waitcnt lgkmcnt(0)
	v_add_f32_e32 v80, v80, v81
	ds_bpermute_b32 v81, v62, v80
	s_waitcnt lgkmcnt(0)
	v_add_f32_e32 v80, v80, v81
	ds_bpermute_b32 v81, v63, v80
	s_waitcnt lgkmcnt(0)
	v_add_f32_e32 v80, v80, v81
	v_fmamk_f32 v80, v80, 0x3a800000, v64
	v_mul_f32_e32 v81, 0x4f800000, v80
	v_cmp_gt_f32_e32 vcc, s17, v80
	s_nop 1
	v_cndmask_b32_e32 v80, v80, v81, vcc
	v_sqrt_f32_e32 v81, v80
	s_nop 0
	v_add_u32_e32 v82, -1, v81
	v_fma_f32 v83, -v82, v81, v80
	v_cmp_ge_f32_e64 s[4:5], 0, v83
	v_add_u32_e32 v83, 1, v81
	s_nop 0
	v_cndmask_b32_e64 v82, v81, v82, s[4:5]
	v_fma_f32 v81, -v83, v81, v80
	v_cmp_lt_f32_e64 s[4:5], 0, v81
	s_nop 1
	v_cndmask_b32_e64 v81, v82, v83, s[4:5]
	v_mul_f32_e32 v82, 0x37800000, v81
	v_cndmask_b32_e32 v81, v81, v82, vcc
	v_cmp_class_f32_e32 vcc, v80, v65
	s_nop 1
	v_cndmask_b32_e32 v80, v81, v80, vcc
	v_div_scale_f32 v81, s[4:5], v80, v80, 1.0
	v_rcp_f32_e32 v82, v81
	s_lshl_b64 s[4:5], s[14:15], 11
	s_sub_i32 s14, s19, s62
	s_cmp_lt_i32 s14, 0x8400
	v_fma_f32 v83, -v81, v82, 1.0
	v_fmac_f32_e32 v82, v83, v82
	v_div_scale_f32 v83, vcc, 1.0, v80, 1.0
	v_mul_f32_e32 v84, v83, v82
	v_fma_f32 v85, -v81, v84, v83
	v_fmac_f32_e32 v84, v85, v82
	v_fma_f32 v81, -v81, v84, v83
	v_div_fmas_f32 v81, v81, v82, v84
	v_div_fixup_f32 v80, v81, v80, 1.0
	v_pk_mul_f32 v[24:25], v[24:25], v[80:81] op_sel_hi:[1,0]
	v_pk_mul_f32 v[22:23], v[22:23], v[80:81] op_sel_hi:[1,0]
	s_waitcnt vmcnt(11)
	v_pk_mul_f32 v[24:25], v[68:69], v[24:25]
	v_pk_mul_f32 v[22:23], v[66:67], v[22:23]
	s_waitcnt vmcnt(10)
	v_pk_add_f32 v[66:67], v[72:73], 1.0 op_sel_hi:[1,0]
	v_pk_add_f32 v[68:69], v[70:71], 1.0 op_sel_hi:[1,0]
	s_waitcnt vmcnt(9)
	v_pk_fma_f32 v[24:25], v[66:67], v[24:25], v[76:77]
	v_pk_fma_f32 v[22:23], v[68:69], v[22:23], v[74:75]
	v_lshl_add_u64 v[82:83], v[56:57], 0, s[4:5]
	v_cvt_pk_bf16_f32 v22, v22, v23
	v_cvt_pk_bf16_f32 v23, v24, v25
	global_store_dwordx2 v[82:83], v[22:23], off
	v_lshl_add_u64 v[84:85], v[78:79], 0, s[10:11]
	v_pk_mul_f32 v[16:17], v[16:17], v[80:81] op_sel_hi:[1,0]
	v_pk_mul_f32 v[14:15], v[14:15], v[80:81] op_sel_hi:[1,0]
	v_pk_mul_f32 v[8:9], v[8:9], v[80:81] op_sel_hi:[1,0]
	v_pk_mul_f32 v[6:7], v[6:7], v[80:81] op_sel_hi:[1,0]
	s_waitcnt vmcnt(9)
	v_pk_mul_f32 v[14:15], v[90:91], v[14:15]
	v_pk_mul_f32 v[16:17], v[92:93], v[16:17]
	s_waitcnt vmcnt(8)
	v_pk_add_f32 v[22:23], v[96:97], 1.0 op_sel_hi:[1,0]
	v_pk_add_f32 v[24:25], v[94:95], 1.0 op_sel_hi:[1,0]
	s_waitcnt vmcnt(7)
	v_pk_fma_f32 v[16:17], v[22:23], v[16:17], v[100:101]
	v_pk_fma_f32 v[14:15], v[24:25], v[14:15], v[98:99]
	s_nop 0
	v_cvt_pk_bf16_f32 v14, v14, v15
	v_cvt_pk_bf16_f32 v15, v16, v17
	global_store_dwordx2 v[82:83], v[14:15], off offset:512
	s_nop 0
	s_waitcnt vmcnt(7)
	v_pk_mul_f32 v[6:7], v[6:7], v[102:103]
	v_pk_mul_f32 v[8:9], v[8:9], v[104:105]
	s_waitcnt vmcnt(6)
	v_pk_add_f32 v[14:15], v[108:109], 1.0 op_sel_hi:[1,0]
	v_pk_add_f32 v[16:17], v[106:107], 1.0 op_sel_hi:[1,0]
	s_waitcnt vmcnt(5)
	v_pk_fma_f32 v[8:9], v[8:9], v[14:15], v[112:113]
	v_pk_fma_f32 v[6:7], v[6:7], v[16:17], v[110:111]
	v_mov_b32_e32 v22, v30
	v_cvt_pk_bf16_f32 v6, v6, v7
	v_cvt_pk_bf16_f32 v7, v8, v9
	global_store_dwordx2 v[82:83], v[6:7], off offset:1024
	v_pk_mul_f32 v[78:79], v[4:5], v[80:81] op_sel_hi:[1,0]
	v_pk_mul_f32 v[80:81], v[2:3], v[80:81] op_sel_hi:[1,0]
	v_mov_b32_e32 v23, v31
	v_mov_b32_e32 v24, v32
	v_mov_b32_e32 v25, v33
	v_mov_b32_e32 v14, v26
	v_mov_b32_e32 v15, v27
	v_mov_b32_e32 v16, v28
	v_mov_b32_e32 v17, v29
	v_mov_b32_e32 v6, v18
	v_mov_b32_e32 v7, v19
	v_mov_b32_e32 v8, v20
	v_mov_b32_e32 v9, v21
	v_mov_b32_e32 v2, v10
	v_mov_b32_e32 v3, v11
	v_mov_b32_e32 v4, v12
	v_mov_b32_e32 v5, v13
	v_mov_b64_e32 v[10:11], v[34:35]
	v_mov_b64_e32 v[18:19], v[38:39]
	v_mov_b64_e32 v[26:27], v[42:43]
	v_mov_b64_e32 v[12:13], v[36:37]
	v_mov_b64_e32 v[20:21], v[40:41]
	v_mov_b64_e32 v[28:29], v[44:45]
	s_waitcnt vmcnt(5)
	v_pk_mul_f32 v[30:31], v[80:81], v[114:115]
	v_pk_mul_f32 v[32:33], v[78:79], v[116:117]
	s_waitcnt vmcnt(4)
	v_pk_add_f32 v[66:67], v[120:121], 1.0 op_sel_hi:[1,0]
	v_pk_add_f32 v[68:69], v[118:119], 1.0 op_sel_hi:[1,0]
	s_waitcnt vmcnt(3)
	v_pk_fma_f32 v[32:33], v[32:33], v[66:67], v[124:125]
	v_pk_fma_f32 v[30:31], v[30:31], v[68:69], v[122:123]
	s_nop 0
	v_cvt_pk_bf16_f32 v30, v30, v31
	v_cvt_pk_bf16_f32 v31, v32, v33
	global_store_dwordx2 v[82:83], v[30:31], off offset:1536
	v_mov_b64_e32 v[30:31], v[46:47]
	v_mov_b64_e32 v[32:33], v[48:49]
	s_cbranch_scc0 .LBB0_165
